# scan producer: k tiles prefetched first and first wait covers only them; remaining raw loads issued after the first-half parameter waits
# speedup vs baseline: 1.0996x; 1.0153x over previous
.LBB0_302:
	s_mov_b32 s96, 32
	s_barrier
	s_cmp_lt_i32 s96, 0
	s_cbranch_scc1 .LBB0_301
	s_ashr_i32 s22, s95, 4
	s_and_b32 s24, s95, 1
	s_bfe_i32 s33, s95, 0x10000
	s_ashr_i32 s23, s22, 31
	s_cmp_eq_u32 s24, 0
	s_cselect_b64 s[56:57], -1, 0
	s_lshl_b32 s58, s95, 5
	s_and_b32 s33, s33, 0x600
	s_and_b32 s60, s58, 0x1c0
	s_or_b32 s33, s33, s60
	s_lshl_b32 s58, s33, 1
	s_mov_b32 s59, s25
	v_or_b32_e32 v148, s60, v140
	v_lshl_add_u64 v[152:153], v[142:143], 0, s[58:59]
	v_readlane_b32 s58, v244, 15
	v_lshlrev_b32_e32 v6, 1, v148
	v_mov_b32_e32 v7, v34
	v_readlane_b32 s59, v244, 16
	v_or_b32_e32 v2, 0x400, v148
	v_or_b32_e32 v4, 0x408, v148
	v_lshl_add_u64 v[154:155], s[58:59], 0, v[6:7]
	v_readlane_b32 s58, v244, 17
	v_readlane_b32 s59, v244, 18
	v_mov_b32_e32 v32, v34
	v_mov_b32_e32 v33, v34
	v_lshl_add_u64 v[156:157], s[58:59], 0, v[6:7]
	v_mov_b32_e32 v35, v34
	v_lshlrev_b32_e32 v181, 2, v2
	v_lshlrev_b32_e32 v182, 2, v4
	v_mov_b64_e32 v[2:3], v[32:33]
	v_mov_b64_e32 v[6:7], v[32:33]
	v_mov_b64_e32 v[10:11], v[32:33]
	v_mov_b64_e32 v[14:15], v[32:33]
	s_mov_b32 s97, 0
	s_lshl_b64 s[22:23], s[22:23], 11
	v_or_b32_e32 v150, 8, v148
	s_lshl_b32 s24, s24, 15
	s_mov_b32 s76, -4
	s_lshl_b32 s77, s60, 2
	v_mov_b32_e32 v183, v173
	v_mov_b32_e32 v184, v172
	v_mov_b64_e32 v[4:5], v[34:35]
	v_mov_b64_e32 v[8:9], v[34:35]
	v_mov_b64_e32 v[12:13], v[34:35]
	v_mov_b64_e32 v[16:17], v[34:35]
	s_and_saveexec_b64 s[98:99], s[38:39]
	s_cbranch_execz .Lspf_skip0
	s_load_dwordx4 s[64:67], s[80:81], 0x80
	s_lshl_b64 s[58:59], s[2:3], 2
	s_waitcnt lgkmcnt(0)
	s_add_u32 s33, s64, s58
	s_addc_u32 s65, s65, s59
	s_add_u32 s64, s33, s77
	s_addc_u32 s65, s65, 0
	s_add_u32 s33, s66, s58
	s_addc_u32 s58, s67, s59
	s_add_u32 s66, s33, s77
	s_addc_u32 s67, s58, 0
	v_lshlrev_b32_e32 v22, 2, v140
	global_load_dwordx4 v[6:9], v22, s[66:67]
	global_load_dwordx4 v[10:13], v22, s[66:67] offset:16
	global_load_dwordx4 v[14:17], v22, s[66:67] offset:32
	global_load_dwordx4 v[174:177], v22, s[66:67] offset:48
	global_load_dwordx4 v[246:249], v22, s[64:65] offset:32
	global_load_dwordx4 v[250:253], v22, s[64:65] offset:48
	v_lshl_add_u32 v22, s97, 6, v151
	v_sub_u32_e32 v23, 0x7ff, v22
	v_cndmask_b32_e64 v24, v23, v22, s[56:57]
	v_ashrrev_i32_e32 v25, 31, v24
	v_lshl_add_u64 v[22:23], s[22:23], 0, v[24:25]
	v_mov_b64_e32 v[26:27], s[30:31]
	v_mad_u64_u32 v[28:29], s[100:101], v22, s89, v[26:27]
	v_mad_i32_i24 v29, v23, s89, v29
	v_lshlrev_b32_e32 v30, 1, v148
	v_mov_b32_e32 v31, v34
	v_lshl_add_u64 v[28:29], v[28:29], 0, v[30:31]
	s_mov_b64 s[100:101], 0x1000
	v_lshl_add_u64 v[30:31], v[28:29], 0, s[100:101]
	s_mov_b64 s[100:101], 0x3000
	v_lshl_add_u64 v[32:33], v[28:29], 0, s[100:101]
	v_lshl_add_u64 v[22:23], v[22:23], 0, s[24:25]
	v_lshlrev_b64 v[22:23], 10, v[22:23]
	v_lshl_add_u64 v[26:27], v[154:155], 0, v[22:23]
	v_lshl_add_u64 v[22:23], v[156:157], 0, v[22:23]
	v_mov_b32_e32 v56, 0
	v_mov_b32_e32 v57, 0
	v_mov_b32_e32 v58, 0
	v_mov_b32_e32 v59, 0
	v_mov_b32_e32 v60, 0
	v_mov_b32_e32 v61, 0
	v_mov_b32_e32 v62, 0
	v_mov_b32_e32 v63, 0
	v_mov_b32_e32 v68, 0
	v_mov_b32_e32 v69, 0
	v_mov_b32_e32 v70, 0
	v_mov_b32_e32 v71, 0
	v_mov_b32_e32 v72, 0
	v_mov_b32_e32 v73, 0
	v_mov_b32_e32 v74, 0
	v_mov_b32_e32 v75, 0
	v_mov_b32_e32 v92, 0
	v_mov_b32_e32 v93, 0
	v_mov_b32_e32 v94, 0
	v_mov_b32_e32 v95, 0
	v_mov_b32_e32 v96, 0
	v_mov_b32_e32 v97, 0
	v_mov_b32_e32 v98, 0
	v_mov_b32_e32 v99, 0
	v_mov_b32_e32 v100, 0
	v_mov_b32_e32 v101, 0
	v_mov_b32_e32 v102, 0
	v_mov_b32_e32 v103, 0
	v_mov_b32_e32 v104, 0
	v_mov_b32_e32 v105, 0
	v_mov_b32_e32 v106, 0
	v_mov_b32_e32 v107, 0
	global_load_dwordx4 v[84:87], v[30:31], off offset:1024
	global_load_dwordx4 v[88:91], v[30:31], off offset:1040
	v_cmp_lt_i32_e32 vcc, 0, v24
	s_and_saveexec_b64 s[100:101], vcc
	global_load_dwordx4 v[96:99], v[28:29], off offset:-2816
	global_load_dwordx4 v[104:107], v[28:29], off offset:-2800
	s_mov_b64 exec, s[100:101]
	v_cmp_gt_i32_e32 vcc, 0x7ff, v24
	s_and_saveexec_b64 s[100:101], vcc
	global_load_dwordx4 v[92:95], v[32:33], off offset:768
	global_load_dwordx4 v[100:103], v[32:33], off offset:784
	s_mov_b64 exec, s[100:101]
	global_load_dwordx4 v[52:55], v[30:31], off
	global_load_dwordx4 v[64:67], v[30:31], off offset:2048
	global_load_dwordx4 v[76:79], v[26:27], off
	global_load_dwordx4 v[80:83], v[22:23], off
	v_cmp_lt_i32_e32 vcc, 0, v24
	s_and_saveexec_b64 s[100:101], vcc
	global_load_dwordx4 v[56:59], v[28:29], off offset:-3840
	global_load_dwordx4 v[68:71], v[28:29], off offset:-1792
	s_mov_b64 exec, s[100:101]
	v_cmp_gt_i32_e32 vcc, 0x7ff, v24
	s_and_saveexec_b64 s[100:101], vcc
	global_load_dwordx4 v[60:63], v[32:33], off offset:-256
	global_load_dwordx4 v[72:75], v[32:33], off offset:1792
	s_mov_b64 exec, s[100:101]

.LBB0_309:
	s_or_b64 exec, exec, s[60:61]
	s_mov_b64 s[98:99], s[58:59]
	s_load_dwordx4 s[68:71], s[80:81], 0x48
	s_load_dwordx4 s[64:67], s[80:81], 0x80
	s_movk_i32 s33, 0x7ff
	v_cmp_gt_i32_e64 s[60:61], s33, v22
	s_and_saveexec_b64 s[84:85], s[60:61]
	s_cbranch_execz .LBB0_311
	v_mov_b32_e32 v43, v34
	v_lshl_add_u64 v[22:23], v[44:45], 0, v[42:43]
	v_add_co_u32_e32 v22, vcc, 0x3000, v22
	s_nop 1
	v_addc_co_u32_e32 v23, vcc, 0, v23, vcc
.LBB0_311:
	s_or_b64 exec, exec, s[84:85]
	s_mov_b64 s[100:101], s[60:61]
	v_lshlrev_b32_e32 v46, 1, v150
	v_mov_b32_e32 v47, v34
	v_lshl_add_u64 v[20:21], v[20:21], 0, v[46:47]
	s_and_saveexec_b64 s[84:85], s[58:59]
	s_cbranch_execz .LBB0_313
	v_mov_b32_e32 v43, v34
	v_lshl_add_u64 v[20:21], v[44:45], 0, v[42:43]

.LBB0_323:
	s_or_b64 exec, exec, s[84:85]
	v_lshl_add_u64 v[18:19], v[18:19], 0, s[24:25]
	v_lshlrev_b64 v[18:19], 10, v[18:19]
	v_mov_b32_e32 v47, v34
	v_lshl_add_u64 v[48:49], v[154:155], 0, v[18:19]
	v_lshl_add_u64 v[50:51], v[156:157], 0, v[18:19]
	v_lshl_add_u64 v[18:19], v[20:21], 0, v[46:47]
	v_mov_b32_e32 v26, 0
	v_mov_b32_e32 v22, 0
	v_mov_b32_e32 v23, 0
	v_mov_b32_e32 v24, 0
	v_mov_b32_e32 v25, 0
	s_and_saveexec_b64 s[84:85], s[58:59]
	s_cbranch_execz .LBB0_325
	v_mov_b32_e32 v43, v34
	v_lshl_add_u64 v[22:23], v[44:45], 0, v[42:43]

.LBB0_327:
	s_or_b64 exec, exec, s[84:85]
	v_mov_b32_e32 v47, v34
	v_lshl_add_u64 v[30:31], v[30:31], 0, v[46:47]
	v_mov_b32_e32 v40, 0
	v_mov_b32_e32 v36, 0
	v_mov_b32_e32 v37, 0
	v_mov_b32_e32 v38, 0
	v_mov_b32_e32 v39, 0
	s_and_saveexec_b64 s[84:85], s[58:59]
	s_cbranch_execz .LBB0_329
	v_mov_b32_e32 v43, v34
	v_lshl_add_u64 v[36:37], v[44:45], 0, v[42:43]

.LBB0_331:
	s_or_b64 exec, exec, s[58:59]
	s_lshl_b32 s33, s97, 2
	s_and_b32 s33, s33, 4
	s_lshl_b64 s[58:59], s[62:63], 2
	s_waitcnt lgkmcnt(0)
	s_add_u32 s60, s68, s58
	s_addc_u32 s61, s69, s59
	v_lshlrev_b32_e32 v160, 2, v148
	s_nop 0
	s_waitcnt vmcnt(8)
	v_cvt_f32_f16_e32 v236, v100
	v_cvt_f32_f16_sdwa v234, v100 dst_sel:DWORD dst_unused:UNUSED_PAD src0_sel:WORD_1
	v_cvt_f32_f16_e32 v232, v101
	v_cvt_f32_f16_sdwa v230, v101 dst_sel:DWORD dst_unused:UNUSED_PAD src0_sel:WORD_1
	v_cvt_f32_f16_e32 v229, v102
	v_cvt_f32_f16_sdwa v227, v102 dst_sel:DWORD dst_unused:UNUSED_PAD src0_sel:WORD_1
	v_cvt_f32_f16_e32 v211, v103
	v_cvt_f32_f16_sdwa v209, v103 dst_sel:DWORD dst_unused:UNUSED_PAD src0_sel:WORD_1
	v_cvt_f32_f16_e32 v109, v92
	v_cvt_f32_f16_sdwa v243, v92 dst_sel:DWORD dst_unused:UNUSED_PAD src0_sel:WORD_1
	v_cvt_f32_f16_e32 v242, v93
	v_cvt_f32_f16_sdwa v205, v93 dst_sel:DWORD dst_unused:UNUSED_PAD src0_sel:WORD_1
	v_cvt_f32_f16_e32 v241, v94
	v_cvt_f32_f16_sdwa v240, v94 dst_sel:DWORD dst_unused:UNUSED_PAD src0_sel:WORD_1
	v_cvt_f32_f16_e32 v239, v95
	v_cvt_f32_f16_sdwa v238, v95 dst_sel:DWORD dst_unused:UNUSED_PAD src0_sel:WORD_1
	global_load_dwordx4 v[92:95], v160, s[60:61] offset:2096
	global_load_dwordx4 v[100:103], v160, s[60:61] offset:2080
	global_load_dwordx4 v[112:115], v160, s[60:61] offset:2064
	global_load_dwordx4 v[128:131], v160, s[60:61] offset:2048
	v_cvt_f32_f16_e32 v235, v104
	v_cvt_f32_f16_sdwa v233, v104 dst_sel:DWORD dst_unused:UNUSED_PAD src0_sel:WORD_1
	v_cvt_f32_f16_e32 v108, v84
	v_cvt_f32_f16_e32 v104, v96
	s_add_u32 s68, s70, s58
	s_addc_u32 s69, s71, s59
	v_cvt_f32_f16_sdwa v196, v96 dst_sel:DWORD dst_unused:UNUSED_PAD src0_sel:WORD_1
	v_sub_f32_e32 v96, v104, v108
	v_cvt_f32_f16_e32 v231, v105
	v_cvt_f32_f16_sdwa v228, v105 dst_sel:DWORD dst_unused:UNUSED_PAD src0_sel:WORD_1
	v_cvt_f32_f16_e32 v226, v106
	v_cvt_f32_f16_sdwa v210, v106 dst_sel:DWORD dst_unused:UNUSED_PAD src0_sel:WORD_1
	v_cvt_f32_f16_e32 v208, v107
	v_cvt_f32_f16_sdwa v206, v107 dst_sel:DWORD dst_unused:UNUSED_PAD src0_sel:WORD_1
	v_cvt_f32_f16_e32 v201, v97
	v_cvt_f32_f16_sdwa v204, v97 dst_sel:DWORD dst_unused:UNUSED_PAD src0_sel:WORD_1
	v_cvt_f32_f16_e32 v203, v98
	v_cvt_f32_f16_sdwa v198, v98 dst_sel:DWORD dst_unused:UNUSED_PAD src0_sel:WORD_1
	v_cvt_f32_f16_e32 v195, v99
	v_cvt_f32_f16_sdwa v237, v99 dst_sel:DWORD dst_unused:UNUSED_PAD src0_sel:WORD_1
	s_lshl_b64 s[58:59], s[2:3], 2
	v_add_u32_e32 v35, s33, v149
	s_add_u32 s33, s64, s58
	s_addc_u32 s65, s65, s59
	s_add_u32 s64, s33, s77
	s_addc_u32 s65, s65, 0
	v_lshlrev_b32_e32 v158, 2, v140
	v_sub_f32_e32 v108, v109, v108
	v_cvt_f32_f16_sdwa v199, v84 dst_sel:DWORD dst_unused:UNUSED_PAD src0_sel:WORD_1
	v_cvt_f32_f16_e32 v200, v85
	v_cvt_f32_f16_sdwa v202, v85 dst_sel:DWORD dst_unused:UNUSED_PAD src0_sel:WORD_1
	v_cvt_f32_f16_e32 v197, v86
	v_cvt_f32_f16_sdwa v194, v86 dst_sel:DWORD dst_unused:UNUSED_PAD src0_sel:WORD_1
	v_cvt_f32_f16_e32 v161, v87
	v_cvt_f32_f16_sdwa v193, v87 dst_sel:DWORD dst_unused:UNUSED_PAD src0_sel:WORD_1
	v_cvt_f32_f16_e32 v192, v88
	v_cvt_f32_f16_sdwa v191, v88 dst_sel:DWORD dst_unused:UNUSED_PAD src0_sel:WORD_1
	v_cvt_f32_f16_e32 v190, v89
	v_cvt_f32_f16_sdwa v189, v89 dst_sel:DWORD dst_unused:UNUSED_PAD src0_sel:WORD_1
	v_cvt_f32_f16_e32 v188, v90
	v_cvt_f32_f16_sdwa v187, v90 dst_sel:DWORD dst_unused:UNUSED_PAD src0_sel:WORD_1
	v_cvt_f32_f16_e32 v186, v91
	v_cvt_f32_f16_sdwa v185, v91 dst_sel:DWORD dst_unused:UNUSED_PAD src0_sel:WORD_1
	v_cmp_lt_i32_e32 vcc, v223, v218
	s_add_u32 s33, s66, s58
	s_addc_u32 s58, s67, s59
	s_add_u32 s66, s33, s77
	s_mov_b32 s33, 0xf800000
	s_addc_u32 s67, s58, 0
	v_lshl_add_u32 v35, v35, 14, 0
	s_waitcnt vmcnt(0)
	v_fma_mix_f32 v159, v96, v128, v84 op_sel_hi:[0,0,1]
	global_load_dwordx4 v[96:99], v160, s[68:69] offset:2096
	global_load_dwordx4 v[104:107], v160, s[68:69] offset:2080
	global_load_dwordx4 v[120:123], v160, s[68:69] offset:2064
	global_load_dwordx4 v[132:135], v160, s[68:69] offset:2048
	v_sub_f32_e32 v128, v196, v199
	v_fma_mix_f32 v196, v128, v129, v84 op_sel:[0,0,1] op_sel_hi:[0,0,1]
	v_sub_f32_e32 v128, v201, v200
	v_fma_mix_f32 v201, v128, v130, v85 op_sel_hi:[0,0,1]
	v_sub_f32_e32 v128, v242, v200
	v_sub_f32_e32 v84, v243, v199
	v_sub_f32_e32 v129, v231, v190
	v_sub_f32_e32 v130, v232, v190
	s_waitcnt vmcnt(0)
	v_fmac_f32_e32 v159, v108, v132
	global_load_dwordx4 v[108:111], v158, s[64:65] offset:48
	global_load_dwordx4 v[116:119], v158, s[64:65] offset:32
	global_load_dwordx4 v[124:127], v158, s[64:65] offset:16
	global_load_dwordx4 v[136:139], v158, s[64:65]
	v_fmac_f32_e32 v201, v128, v134
	v_sub_f32_e32 v128, v204, v202
	v_fma_mix_f32 v204, v128, v131, v85 op_sel:[0,0,1] op_sel_hi:[0,0,1]
	v_sub_f32_e32 v85, v205, v202
	v_fmac_f32_e32 v204, v85, v135
	v_sub_f32_e32 v85, v203, v197
	v_fmac_f32_e32 v196, v84, v133
	v_fma_mix_f32 v202, v85, v112, v86 op_sel_hi:[0,0,1]
	v_sub_f32_e32 v85, v241, v197
	v_fmac_f32_e32 v202, v85, v120
	v_sub_f32_e32 v85, v198, v194
	v_fma_mix_f32 v197, v85, v113, v86 op_sel:[0,0,1] op_sel_hi:[0,0,1]
	v_sub_f32_e32 v85, v240, v194
	v_fmac_f32_e32 v197, v85, v121
	v_sub_f32_e32 v85, v195, v161
	v_fma_mix_f32 v194, v85, v114, v87 op_sel_hi:[0,0,1]
	v_sub_f32_e32 v85, v239, v161
	v_fmac_f32_e32 v194, v85, v122
	v_sub_f32_e32 v85, v237, v193
	v_fma_mix_f32 v161, v85, v115, v87 op_sel:[0,0,1] op_sel_hi:[0,0,1]
	v_sub_f32_e32 v85, v238, v193
	v_sub_f32_e32 v134, v235, v192
	v_fmac_f32_e32 v161, v85, v123
	v_fma_mix_f32 v85, v134, v100, v88 op_sel_hi:[0,0,1]
	v_sub_f32_e32 v133, v236, v192
	v_fmac_f32_e32 v85, v133, v104
	v_sub_f32_e32 v131, v233, v191
	v_sub_f32_e32 v132, v234, v191
	v_sub_f32_e32 v128, v230, v189
	v_sub_f32_e32 v123, v210, v187
	v_sub_f32_e32 v121, v208, v186
	v_sub_f32_e32 v122, v211, v186
	v_sub_f32_e32 v120, v209, v185
	v_cvt_f32_f16_e32 v104, v68
	v_lshl_add_u32 v135, v141, 1, v35
	s_waitcnt vmcnt(2)
	v_mul_f32_e32 v85, v116, v85
	s_waitcnt vmcnt(1)
	v_mul_f32_e32 v203, v124, v202
	s_waitcnt vmcnt(0)
	v_mul_f32_e32 v199, v137, v196
	v_mul_f32_e32 v207, v136, v159
	v_mul_f32_e32 v84, v199, v199
	v_fmac_f32_e32 v84, v207, v207
	v_mul_f32_e32 v200, v138, v201
	v_fmac_f32_e32 v84, v200, v200
	v_mul_f32_e32 v205, v139, v204
	v_fmac_f32_e32 v84, v205, v205
	v_fmac_f32_e32 v84, v203, v203
	v_mul_f32_e32 v198, v125, v197
	v_fmac_f32_e32 v84, v198, v198
	v_mul_f32_e32 v195, v126, v194
	v_fmac_f32_e32 v84, v195, v195
	v_mul_f32_e32 v193, v127, v161
	v_fmac_f32_e32 v84, v193, v193
	v_fmac_f32_e32 v84, v85, v85
	v_fma_mix_f32 v85, v131, v101, v88 op_sel:[0,0,1] op_sel_hi:[0,0,1]
	v_fmac_f32_e32 v85, v132, v105
	v_mul_f32_e32 v85, v117, v85
	v_fmac_f32_e32 v84, v85, v85
	v_fma_mix_f32 v85, v129, v102, v89 op_sel_hi:[0,0,1]
	v_fmac_f32_e32 v85, v130, v106
	v_mul_f32_e32 v85, v118, v85
	v_sub_f32_e32 v127, v228, v189
	v_fmac_f32_e32 v84, v85, v85
	v_fma_mix_f32 v85, v127, v103, v89 op_sel:[0,0,1] op_sel_hi:[0,0,1]
	v_fmac_f32_e32 v85, v128, v107
	v_mul_f32_e32 v85, v119, v85
	v_sub_f32_e32 v125, v226, v188
	v_fmac_f32_e32 v84, v85, v85
	v_fma_mix_f32 v85, v125, v92, v90 op_sel_hi:[0,0,1]
	v_sub_f32_e32 v126, v229, v188
	v_fmac_f32_e32 v85, v126, v96
	v_mul_f32_e32 v85, v108, v85
	v_fmac_f32_e32 v84, v85, v85
	v_fma_mix_f32 v85, v123, v93, v90 op_sel:[0,0,1] op_sel_hi:[0,0,1]
	v_sub_f32_e32 v124, v227, v187
	v_fmac_f32_e32 v85, v124, v97
	v_mul_f32_e32 v85, v109, v85
	v_fmac_f32_e32 v84, v85, v85
	v_fma_mix_f32 v85, v121, v94, v91 op_sel_hi:[0,0,1]
	v_fmac_f32_e32 v85, v122, v98
	v_mul_f32_e32 v85, v110, v85
	v_sub_f32_e32 v119, v206, v185
	v_fmac_f32_e32 v84, v85, v85
	v_fma_mix_f32 v85, v119, v95, v91 op_sel:[0,0,1] op_sel_hi:[0,0,1]
	v_fmac_f32_e32 v85, v120, v99
	v_mul_f32_e32 v85, v111, v85
	v_fmac_f32_e32 v84, v85, v85
	v_cndmask_b32_e32 v85, v217, v223, vcc
	v_lshlrev_b32_e32 v85, 2, v85
	ds_bpermute_b32 v85, v85, v84
	v_cmp_lt_i32_e32 vcc, v224, v218
	v_cvt_f32_f16_e32 v117, v64
	v_cvt_f32_f16_e32 v116, v72
	v_cvt_f32_f16_e32 v137, v76
	s_waitcnt lgkmcnt(0)
	v_add_f32_e32 v84, v84, v85
	v_cndmask_b32_e32 v85, v217, v224, vcc
	v_lshlrev_b32_e32 v85, 2, v85
	ds_bpermute_b32 v85, v85, v84
	v_sub_f32_e32 v104, v104, v117
	v_add3_u32 v206, v35, v178, v179
	s_waitcnt lgkmcnt(0)
	v_add_f32_e32 v84, v84, v85
	v_cmp_gt_f32_e32 vcc, s33, v84
	v_mul_f32_e32 v85, 0x4f800000, v84
	s_nop 0
	v_cndmask_b32_e32 v84, v84, v85, vcc
	v_sqrt_f32_e32 v85, v84
	s_nop 0
	v_add_u32_e32 v86, -1, v85
	v_fma_f32 v87, -v86, v85, v84
	v_cmp_ge_f32_e64 s[58:59], 0, v87
	v_add_u32_e32 v87, 1, v85
	s_nop 0
	v_cndmask_b32_e64 v86, v85, v86, s[58:59]
	v_fma_f32 v85, -v87, v85, v84
	v_cmp_lt_f32_e64 s[58:59], 0, v85
	s_nop 1
	v_cndmask_b32_e64 v85, v86, v87, s[58:59]
	v_mul_f32_e32 v86, 0x37800000, v85
	v_cndmask_b32_e32 v85, v85, v86, vcc
	v_cmp_class_f32_e32 vcc, v84, v214
	s_nop 1
	v_cndmask_b32_e32 v84, v85, v84, vcc
	v_max_f32_e32 v84, 0x2b8cbccc, v84
	v_rcp_f32_e32 v118, v84
	global_load_dwordx4 v[96:99], v160, s[60:61] offset:16
	global_load_dwordx4 v[84:87], v160, s[60:61]
	global_load_dwordx4 v[92:95], v160, s[68:69] offset:16
	global_load_dwordx4 v[88:91], v160, s[68:69]
	global_load_dwordx4 v[100:103], v181, s[60:61] offset:16
	global_load_dwordx4 v[108:111], v181, s[60:61]
	v_mul_f32_e32 v138, v207, v118
	s_waitcnt vmcnt(0)
	v_fma_mix_f32 v208, v104, v108, v64 op_sel_hi:[0,0,1]
	global_load_dwordx4 v[104:107], v181, s[68:69] offset:16
	global_load_dwordx4 v[112:115], v181, s[68:69]
	v_sub_f32_e32 v108, v116, v117
	v_cvt_f32_f16_e32 v116, v80
	s_waitcnt vmcnt(0)
	global_load_dwordx4 v[18:21], v[18:19], off
	s_and_saveexec_b64 s[84:85], s[98:99]
	global_load_dwordx4 v[22:25], v[22:23], off offset:-3824
	global_load_dwordx4 v[36:39], v[36:37], off offset:-1776
	s_or_b64 exec, exec, s[84:85]
	s_and_saveexec_b64 s[84:85], s[100:101]
	global_load_dwordx4 v[26:29], v[26:27], off offset:3840
	global_load_dwordx4 v[40:43], v[40:41], off offset:1792
	s_or_b64 exec, exec, s[84:85]
	global_load_dwordx4 v[30:33], v[30:31], off
	global_load_dwordx4 v[44:47], v[48:49], off offset:16
	global_load_dwordx4 v[48:51], v[50:51], off offset:16
	s_nop 4
	v_fmac_f32_e32 v208, v108, v112
	v_add_f32_dpp v108, v137, v137 row_shr:1 row_mask:0xf bank_mask:0xf bound_ctrl:1
	v_mul_f32_e32 v112, v138, v116
	v_add_f32_e32 v116, -1.0, v116
	v_add_f32_dpp v108, v108, v108 row_shr:2 row_mask:0xf bank_mask:0xf bound_ctrl:1
	v_fma_f32 v116, v116, v6, 1.0
	v_mul_f32_e32 v139, v159, v116
	v_add_f32_dpp v108, v108, v108 row_shr:4 row_mask:0xf bank_mask:0xf bound_ctrl:1
	v_add_u32_e32 v159, v206, v166
	s_nop 0
	v_add_f32_dpp v136, v108, v108 row_shr:8 row_mask:0xf bank_mask:0xf bound_ctrl:1
	s_nop 1
	v_mov_b32_dpp v108, v136 row_newbcast:15 row_mask:0xf bank_mask:0xf bound_ctrl:1
	v_sub_f32_e32 v116, v136, v108
	v_mul_f32_e32 v116, 0x3fb8aa3b, v116
	v_exp_f32_e32 v116, v116
	s_nop 0
	v_mul_f32_e32 v117, v112, v116
	v_mul_f32_e32 v116, v116, v139
	v_cvt_pk_bf16_f32 v117, v117, s0
	v_cvt_pk_bf16_f32 v116, v116, s0
	ds_write_b16 v159, v117 offset:4608
	ds_write_b16 v159, v116 offset:4616
	v_cvt_pk_bf16_f32 v116, v208, s0
	v_add_u32_e32 v117, v135, v167
	ds_write_b16 v117, v116 offset:9728
	s_and_saveexec_b64 s[58:59], s[40:41]
	s_cbranch_execz .LBB0_333
	v_mul_f32_e32 v108, 0xbfb8aa3b, v108
	v_exp_f32_e32 v108, v108
	v_lshl_add_u32 v116, v140, 2, v35
	ds_write_b32 v116, v108 offset:12800
.LBB0_333:
	s_or_b64 exec, exec, s[58:59]
	v_cvt_f32_f16_sdwa v108, v64 dst_sel:DWORD dst_unused:UNUSED_PAD src0_sel:WORD_1
	v_cvt_f32_f16_sdwa v68, v68 dst_sel:DWORD dst_unused:UNUSED_PAD src0_sel:WORD_1
	v_cvt_f32_f16_sdwa v72, v72 dst_sel:DWORD dst_unused:UNUSED_PAD src0_sel:WORD_1
	v_mov_b32_e32 v159, v34
	v_lshl_add_u64 v[116:117], s[66:67], 0, v[158:159]
	v_sub_f32_e32 v68, v68, v108
	v_fma_mix_f32 v207, v68, v109, v64 op_sel:[0,0,1] op_sel_hi:[0,0,1]
	v_sub_f32_e32 v64, v72, v108
	v_fmac_f32_e32 v207, v64, v113
	v_cvt_f32_f16_sdwa v113, v76 dst_sel:DWORD dst_unused:UNUSED_PAD src0_sel:WORD_1
	v_cvt_f32_f16_sdwa v76, v80 dst_sel:DWORD dst_unused:UNUSED_PAD src0_sel:WORD_1
	v_mul_f32_e32 v80, v199, v118
	v_add_u32_e32 v109, v206, v168
	v_add_f32_dpp v64, v113, v113 row_shr:1 row_mask:0xf bank_mask:0xf bound_ctrl:1
	s_nop 1
	v_add_f32_dpp v64, v64, v64 row_shr:2 row_mask:0xf bank_mask:0xf bound_ctrl:1
	s_nop 1
	v_add_f32_dpp v64, v64, v64 row_shr:4 row_mask:0xf bank_mask:0xf bound_ctrl:1
	s_nop 1
	v_add_f32_dpp v68, v64, v64 row_shr:8 row_mask:0xf bank_mask:0xf bound_ctrl:1
	v_mul_f32_e32 v64, v80, v76
	v_add_f32_e32 v76, -1.0, v76
	v_mov_b32_dpp v72, v68 row_newbcast:15 row_mask:0xf bank_mask:0xf bound_ctrl:1
	v_fma_f32 v76, v76, v7, 1.0
	v_mul_f32_e32 v196, v196, v76
	v_sub_f32_e32 v76, v68, v72
	v_mul_f32_e32 v76, 0x3fb8aa3b, v76
	v_exp_f32_e32 v76, v76
	s_nop 0
	v_mul_f32_e32 v108, v64, v76
	v_mul_f32_e32 v76, v76, v196
	v_cvt_pk_bf16_f32 v108, v108, s0
	v_cvt_pk_bf16_f32 v76, v76, s0
	ds_write_b16 v109, v108 offset:4608
	ds_write_b16 v109, v76 offset:4616
	v_cvt_pk_bf16_f32 v76, v207, s0
	v_add_u32_e32 v108, v135, v169
	ds_write_b16 v108, v76 offset:9728
	s_and_saveexec_b64 s[58:59], s[40:41]
	s_cbranch_execz .LBB0_335
	v_mul_f32_e32 v72, 0xbfb8aa3b, v72
	v_exp_f32_e32 v72, v72
	v_lshl_add_u32 v76, v140, 2, v35
	ds_write_b32 v76, v72 offset:12804
.LBB0_335:
	s_or_b64 exec, exec, s[58:59]
	v_cvt_f32_f16_e32 v72, v65
	v_cvt_f32_f16_e32 v76, v69
	v_cvt_f32_f16_e32 v199, v73
	v_cvt_f32_f16_e32 v206, v81
	v_mul_f32_e32 v200, v200, v118
	v_sub_f32_e32 v76, v76, v72
	v_sub_f32_e32 v72, v199, v72
	v_cvt_f32_f16_e32 v199, v77
	v_fma_mix_f32 v76, v76, v110, v65 op_sel_hi:[0,0,1]
	v_fmac_f32_e32 v76, v72, v114
	v_mul_f32_e32 v110, v200, v206
	v_add_f32_dpp v72, v199, v199 row_shr:1 row_mask:0xf bank_mask:0xf bound_ctrl:1
	v_add_f32_e32 v206, -1.0, v206
	v_cvt_pk_bf16_f32 v76, v76, s0
	v_add_f32_dpp v72, v72, v72 row_shr:2 row_mask:0xf bank_mask:0xf bound_ctrl:1
	v_fma_f32 v206, v206, v8, 1.0
	v_add_f32_dpp v72, v72, v72 row_shr:4 row_mask:0xf bank_mask:0xf bound_ctrl:1
	v_mul_f32_e32 v201, v201, v206
	s_nop 0
	v_add_f32_dpp v114, v72, v72 row_shr:8 row_mask:0xf bank_mask:0xf bound_ctrl:1
	s_nop 1
	v_mov_b32_dpp v72, v114 row_newbcast:15 row_mask:0xf bank_mask:0xf bound_ctrl:1
	v_sub_f32_e32 v206, v114, v72
	v_mul_f32_e32 v206, 0x3fb8aa3b, v206
	v_exp_f32_e32 v206, v206
	s_nop 0
	v_mul_f32_e32 v207, v110, v206
	v_mul_f32_e32 v206, v206, v201
	v_cvt_pk_bf16_f32 v207, v207, s0
	v_cvt_pk_bf16_f32 v206, v206, s0
	ds_write_b16 v109, v207 offset:4688
	ds_write_b16 v109, v206 offset:4696
	ds_write_b16 v108, v76 offset:9776
	s_and_saveexec_b64 s[58:59], s[40:41]
	s_cbranch_execz .LBB0_337
	v_mul_f32_e32 v72, 0xbfb8aa3b, v72
	v_exp_f32_e32 v72, v72
	v_lshl_add_u32 v76, v140, 2, v35
	ds_write_b32 v76, v72 offset:12808
.LBB0_337:
	s_or_b64 exec, exec, s[58:59]
	v_cvt_f32_f16_sdwa v72, v65 dst_sel:DWORD dst_unused:UNUSED_PAD src0_sel:WORD_1
	v_cvt_f32_f16_sdwa v69, v69 dst_sel:DWORD dst_unused:UNUSED_PAD src0_sel:WORD_1
	v_cvt_f32_f16_sdwa v73, v73 dst_sel:DWORD dst_unused:UNUSED_PAD src0_sel:WORD_1
	v_sub_f32_e32 v69, v69, v72
	v_fma_mix_f32 v76, v69, v111, v65 op_sel:[0,0,1] op_sel_hi:[0,0,1]
	v_cvt_f32_f16_sdwa v111, v77 dst_sel:DWORD dst_unused:UNUSED_PAD src0_sel:WORD_1
	v_sub_f32_e32 v65, v73, v72
	v_cvt_f32_f16_sdwa v73, v81 dst_sel:DWORD dst_unused:UNUSED_PAD src0_sel:WORD_1
	v_fmac_f32_e32 v76, v65, v115
	v_add_f32_dpp v65, v111, v111 row_shr:1 row_mask:0xf bank_mask:0xf bound_ctrl:1
	v_mul_f32_e32 v81, v205, v118
	s_nop 0
	v_add_f32_dpp v65, v65, v65 row_shr:2 row_mask:0xf bank_mask:0xf bound_ctrl:1
	s_nop 1
	v_add_f32_dpp v65, v65, v65 row_shr:4 row_mask:0xf bank_mask:0xf bound_ctrl:1
	s_nop 1
	v_add_f32_dpp v69, v65, v65 row_shr:8 row_mask:0xf bank_mask:0xf bound_ctrl:1
	v_mul_f32_e32 v65, v81, v73
	v_add_f32_e32 v73, -1.0, v73
	v_mov_b32_dpp v72, v69 row_newbcast:15 row_mask:0xf bank_mask:0xf bound_ctrl:1
	v_fma_f32 v73, v73, v9, 1.0
	v_mul_f32_e32 v115, v204, v73
	v_sub_f32_e32 v73, v69, v72
	v_mul_f32_e32 v73, 0x3fb8aa3b, v73
	v_exp_f32_e32 v73, v73
	s_nop 0
	v_mul_f32_e32 v77, v65, v73
	v_mul_f32_e32 v73, v73, v115
	v_cvt_pk_bf16_f32 v73, v73, s0
	v_cvt_pk_bf16_f32 v77, v77, s0
	ds_write_b16 v109, v73 offset:4776
	v_cvt_pk_bf16_f32 v73, v76, s0
	ds_write_b16 v109, v77 offset:4768
	ds_write_b16 v108, v73 offset:9824
	s_and_saveexec_b64 s[58:59], s[40:41]
	s_cbranch_execz .LBB0_339
	v_mul_f32_e32 v72, 0xbfb8aa3b, v72
	v_exp_f32_e32 v72, v72
	v_lshl_add_u32 v73, v140, 2, v35
	ds_write_b32 v73, v72 offset:12812
.LBB0_339:
	s_or_b64 exec, exec, s[58:59]
	v_cvt_f32_f16_e32 v72, v66
	v_cvt_f32_f16_e32 v73, v70
	v_cvt_f32_f16_e32 v76, v74
	v_cvt_f32_f16_e32 v205, v78
	v_mul_f32_e32 v203, v203, v118
	v_sub_f32_e32 v73, v73, v72
	v_fma_mix_f32 v73, v73, v100, v66 op_sel_hi:[0,0,1]
	v_sub_f32_e32 v72, v76, v72
	v_cvt_f32_f16_e32 v76, v82
	v_fmac_f32_e32 v73, v72, v104
	v_add_f32_dpp v72, v205, v205 row_shr:1 row_mask:0xf bank_mask:0xf bound_ctrl:1
	v_cvt_pk_bf16_f32 v73, v73, s0
	v_mul_f32_e32 v104, v203, v76
	v_add_f32_dpp v72, v72, v72 row_shr:2 row_mask:0xf bank_mask:0xf bound_ctrl:1
	v_add_f32_e32 v76, -1.0, v76
	v_fma_f32 v76, v76, v10, 1.0
	v_add_f32_dpp v72, v72, v72 row_shr:4 row_mask:0xf bank_mask:0xf bound_ctrl:1
	v_mul_f32_e32 v202, v202, v76
	s_nop 0
	v_add_f32_dpp v204, v72, v72 row_shr:8 row_mask:0xf bank_mask:0xf bound_ctrl:1
	s_nop 1
	v_mov_b32_dpp v72, v204 row_newbcast:15 row_mask:0xf bank_mask:0xf bound_ctrl:1
	v_sub_f32_e32 v76, v204, v72
	v_mul_f32_e32 v76, 0x3fb8aa3b, v76
	v_exp_f32_e32 v76, v76
	s_nop 0
	v_mul_f32_e32 v77, v104, v76
	v_mul_f32_e32 v76, v76, v202
	v_cvt_pk_bf16_f32 v77, v77, s0
	v_cvt_pk_bf16_f32 v76, v76, s0
	ds_write_b16 v109, v77 offset:4848
	ds_write_b16 v109, v76 offset:4856
	ds_write_b16 v108, v73 offset:9872
	s_and_saveexec_b64 s[58:59], s[40:41]
	s_cbranch_execz .LBB0_341
	v_mul_f32_e32 v72, 0xbfb8aa3b, v72
	v_exp_f32_e32 v72, v72
	v_lshl_add_u32 v73, v140, 2, v35
	ds_write_b32 v73, v72 offset:12816
.LBB0_341:
	s_or_b64 exec, exec, s[58:59]
	v_cvt_f32_f16_sdwa v72, v66 dst_sel:DWORD dst_unused:UNUSED_PAD src0_sel:WORD_1
	v_cvt_f32_f16_sdwa v70, v70 dst_sel:DWORD dst_unused:UNUSED_PAD src0_sel:WORD_1
	v_cvt_f32_f16_sdwa v73, v74 dst_sel:DWORD dst_unused:UNUSED_PAD src0_sel:WORD_1
	v_cvt_f32_f16_sdwa v74, v78 dst_sel:DWORD dst_unused:UNUSED_PAD src0_sel:WORD_1
	v_mul_f32_e32 v78, v198, v118
	v_sub_f32_e32 v70, v70, v72
	v_fma_mix_f32 v76, v70, v101, v66 op_sel:[0,0,1] op_sel_hi:[0,0,1]
	v_sub_f32_e32 v66, v73, v72
	v_cvt_f32_f16_sdwa v73, v82 dst_sel:DWORD dst_unused:UNUSED_PAD src0_sel:WORD_1
	v_fmac_f32_e32 v76, v66, v105
	v_add_f32_dpp v66, v74, v74 row_shr:1 row_mask:0xf bank_mask:0xf bound_ctrl:1
	s_nop 1
	v_add_f32_dpp v66, v66, v66 row_shr:2 row_mask:0xf bank_mask:0xf bound_ctrl:1
	s_nop 1
	v_add_f32_dpp v66, v66, v66 row_shr:4 row_mask:0xf bank_mask:0xf bound_ctrl:1
	s_nop 1
	v_add_f32_dpp v70, v66, v66 row_shr:8 row_mask:0xf bank_mask:0xf bound_ctrl:1
	v_mul_f32_e32 v66, v78, v73
	v_add_f32_e32 v73, -1.0, v73
	v_mov_b32_dpp v72, v70 row_newbcast:15 row_mask:0xf bank_mask:0xf bound_ctrl:1
	v_fma_f32 v73, v73, v11, 1.0
	v_mul_f32_e32 v82, v197, v73
	v_sub_f32_e32 v73, v70, v72
	v_mul_f32_e32 v73, 0x3fb8aa3b, v73
	v_exp_f32_e32 v73, v73
	s_nop 0
	v_mul_f32_e32 v77, v66, v73
	v_mul_f32_e32 v73, v73, v82
	v_cvt_pk_bf16_f32 v73, v73, s0
	v_cvt_pk_bf16_f32 v77, v77, s0
	ds_write_b16 v109, v73 offset:4936
	v_cvt_pk_bf16_f32 v73, v76, s0
	ds_write_b16 v109, v77 offset:4928
	ds_write_b16 v108, v73 offset:9920
	s_and_saveexec_b64 s[58:59], s[40:41]
	s_cbranch_execz .LBB0_343
	v_mul_f32_e32 v72, 0xbfb8aa3b, v72
	v_exp_f32_e32 v72, v72
	v_lshl_add_u32 v73, v140, 2, v35
	ds_write_b32 v73, v72 offset:12820
.LBB0_343:
	s_or_b64 exec, exec, s[58:59]
	v_cvt_f32_f16_e32 v72, v67
	v_cvt_f32_f16_e32 v73, v71
	v_cvt_f32_f16_e32 v76, v75
	v_mul_f32_e32 v195, v195, v118
	v_sub_f32_e32 v73, v73, v72
	v_fma_mix_f32 v73, v73, v102, v67 op_sel_hi:[0,0,1]
	v_sub_f32_e32 v72, v76, v72
	v_fmac_f32_e32 v73, v72, v106
	v_cvt_f32_f16_e32 v106, v79
	v_cvt_f32_f16_e32 v76, v83
	v_cvt_pk_bf16_f32 v73, v73, s0
	v_add_f32_dpp v72, v106, v106 row_shr:1 row_mask:0xf bank_mask:0xf bound_ctrl:1
	v_mul_f32_e32 v102, v195, v76
	s_nop 0
	v_add_f32_dpp v72, v72, v72 row_shr:2 row_mask:0xf bank_mask:0xf bound_ctrl:1
	v_add_f32_e32 v76, -1.0, v76
	v_fma_f32 v76, v76, v12, 1.0
	v_add_f32_dpp v72, v72, v72 row_shr:4 row_mask:0xf bank_mask:0xf bound_ctrl:1
	v_mul_f32_e32 v194, v194, v76
	s_nop 0
	v_add_f32_dpp v105, v72, v72 row_shr:8 row_mask:0xf bank_mask:0xf bound_ctrl:1
	s_nop 1
	v_mov_b32_dpp v72, v105 row_newbcast:15 row_mask:0xf bank_mask:0xf bound_ctrl:1
	v_sub_f32_e32 v76, v105, v72
	v_mul_f32_e32 v76, 0x3fb8aa3b, v76
	v_exp_f32_e32 v76, v76
	s_nop 0
	v_mul_f32_e32 v77, v102, v76
	v_mul_f32_e32 v76, v76, v194
	v_cvt_pk_bf16_f32 v77, v77, s0
	v_cvt_pk_bf16_f32 v76, v76, s0
	ds_write_b16 v109, v77 offset:5008
	ds_write_b16 v109, v76 offset:5016
	ds_write_b16 v108, v73 offset:9968
	s_and_saveexec_b64 s[58:59], s[40:41]
	s_cbranch_execz .LBB0_345
	v_mul_f32_e32 v72, 0xbfb8aa3b, v72
	v_exp_f32_e32 v72, v72
	v_lshl_add_u32 v73, v140, 2, v35
	ds_write_b32 v73, v72 offset:12824
.LBB0_345:
	s_or_b64 exec, exec, s[58:59]
	v_cvt_f32_f16_sdwa v72, v67 dst_sel:DWORD dst_unused:UNUSED_PAD src0_sel:WORD_1
	v_cvt_f32_f16_sdwa v71, v71 dst_sel:DWORD dst_unused:UNUSED_PAD src0_sel:WORD_1
	v_cvt_f32_f16_sdwa v73, v75 dst_sel:DWORD dst_unused:UNUSED_PAD src0_sel:WORD_1
	v_cvt_f32_f16_sdwa v75, v79 dst_sel:DWORD dst_unused:UNUSED_PAD src0_sel:WORD_1
	v_mul_f32_e32 v79, v193, v118
	v_sub_f32_e32 v71, v71, v72
	v_fma_mix_f32 v76, v71, v103, v67 op_sel:[0,0,1] op_sel_hi:[0,0,1]
	v_sub_f32_e32 v67, v73, v72
	v_cvt_f32_f16_sdwa v73, v83 dst_sel:DWORD dst_unused:UNUSED_PAD src0_sel:WORD_1
	v_fmac_f32_e32 v76, v67, v107
	v_add_f32_dpp v67, v75, v75 row_shr:1 row_mask:0xf bank_mask:0xf bound_ctrl:1
	s_nop 1
	v_add_f32_dpp v67, v67, v67 row_shr:2 row_mask:0xf bank_mask:0xf bound_ctrl:1
	s_nop 1
	v_add_f32_dpp v67, v67, v67 row_shr:4 row_mask:0xf bank_mask:0xf bound_ctrl:1
	s_nop 1
	v_add_f32_dpp v71, v67, v67 row_shr:8 row_mask:0xf bank_mask:0xf bound_ctrl:1
	v_mul_f32_e32 v67, v79, v73
	v_add_f32_e32 v73, -1.0, v73
	v_mov_b32_dpp v72, v71 row_newbcast:15 row_mask:0xf bank_mask:0xf bound_ctrl:1
	v_fma_f32 v73, v73, v13, 1.0
	v_mul_f32_e32 v83, v161, v73
	v_sub_f32_e32 v73, v71, v72
	v_mul_f32_e32 v73, 0x3fb8aa3b, v73
	v_exp_f32_e32 v73, v73
	s_nop 0
	v_mul_f32_e32 v77, v67, v73
	v_mul_f32_e32 v73, v73, v83
	v_cvt_pk_bf16_f32 v73, v73, s0
	v_cvt_pk_bf16_f32 v77, v77, s0
	ds_write_b16 v109, v73 offset:5096
	v_cvt_pk_bf16_f32 v73, v76, s0
	ds_write_b16 v109, v77 offset:5088
	ds_write_b16 v108, v73 offset:10016
	s_and_saveexec_b64 s[58:59], s[40:41]
	s_cbranch_execz .LBB0_347
	v_mul_f32_e32 v72, 0xbfb8aa3b, v72
	v_exp_f32_e32 v72, v72
	v_lshl_add_u32 v73, v140, 2, v35
	ds_write_b32 v73, v72 offset:12828
.LBB0_347:
	s_or_b64 exec, exec, s[58:59]
	v_cvt_f32_f16_sdwa v103, v55 dst_sel:DWORD dst_unused:UNUSED_PAD src0_sel:WORD_1
	v_cvt_f32_f16_sdwa v107, v59 dst_sel:DWORD dst_unused:UNUSED_PAD src0_sel:WORD_1
	v_lshl_add_u64 v[100:101], s[64:65], 0, v[158:159]
	v_cvt_f32_f16_sdwa v158, v63 dst_sel:DWORD dst_unused:UNUSED_PAD src0_sel:WORD_1
	v_sub_f32_e32 v75, v75, v71
	v_sub_f32_e32 v107, v107, v103
	v_fma_mix_f32 v99, v107, v99, v55 op_sel:[0,0,1] op_sel_hi:[0,0,1]
	v_sub_f32_e32 v103, v158, v103
	v_fmac_f32_e32 v99, v103, v95
	v_mul_f32_e32 v95, 0x3fb8aa3b, v71
	v_mul_f32_e32 v75, 0x3fb8aa3b, v75
	v_exp_f32_e32 v95, v95
	v_exp_f32_e32 v75, v75
	v_cvt_f32_f16_e32 v59, v59
	v_cvt_f32_f16_e32 v63, v63
	v_mul_f32_e32 v67, v67, v95
	v_mul_f32_e32 v75, v79, v75
	v_mul_f32_e32 v79, v95, v83
	v_cvt_f32_f16_e32 v83, v55
	v_cvt_f32_f16_sdwa v95, v58 dst_sel:DWORD dst_unused:UNUSED_PAD src0_sel:WORD_1
	v_sub_f32_e32 v74, v74, v70
	v_mul_f32_e32 v74, 0x3fb8aa3b, v74
	v_sub_f32_e32 v59, v59, v83
	v_fma_mix_f32 v55, v59, v98, v55 op_sel_hi:[0,0,1]
	v_sub_f32_e32 v59, v63, v83
	v_mul_f32_e32 v83, 0xbfb8aa3b, v105
	v_exp_f32_e32 v83, v83
	v_fmac_f32_e32 v55, v59, v94
	v_cvt_f32_f16_sdwa v98, v62 dst_sel:DWORD dst_unused:UNUSED_PAD src0_sel:WORD_1
	v_exp_f32_e32 v74, v74
	v_mul_f32_e32 v83, v55, v83
	v_cvt_f32_f16_sdwa v55, v54 dst_sel:DWORD dst_unused:UNUSED_PAD src0_sel:WORD_1
	v_cvt_f32_f16_e32 v58, v58
	v_mul_f32_e32 v74, v78, v74
	v_cvt_f32_f16_e32 v62, v62
	v_sub_f32_e32 v95, v95, v55
	v_fma_mix_f32 v95, v95, v97, v54 op_sel:[0,0,1] op_sel_hi:[0,0,1]
	v_sub_f32_e32 v55, v98, v55
	v_fmac_f32_e32 v95, v55, v93
	v_mul_f32_e32 v55, 0x3fb8aa3b, v70
	v_exp_f32_e32 v55, v55
	v_cvt_f32_f16_sdwa v93, v61 dst_sel:DWORD dst_unused:UNUSED_PAD src0_sel:WORD_1
	v_mul_f32_e32 v59, 0x3fb8aa3b, v105
	v_exp_f32_e32 v59, v59
	v_mul_f32_e32 v66, v66, v55
	v_mul_f32_e32 v78, v55, v82
	v_cvt_f32_f16_e32 v55, v54
	v_mul_f32_e32 v94, v102, v59
	v_sub_f32_e32 v63, v106, v105
	v_mul_f32_e32 v63, 0x3fb8aa3b, v63
	v_sub_f32_e32 v58, v58, v55
	v_fma_mix_f32 v54, v58, v96, v54 op_sel_hi:[0,0,1]
	v_sub_f32_e32 v55, v62, v55
	v_fmac_f32_e32 v54, v55, v92
	v_mul_f32_e32 v55, 0x3fb8aa3b, v204
	v_mul_f32_e32 v62, 0xbfb8aa3b, v204
	v_exp_f32_e32 v55, v55
	v_exp_f32_e32 v62, v62
	v_sub_f32_e32 v58, v205, v204
	v_mul_f32_e32 v58, 0x3fb8aa3b, v58
	v_mul_f32_e32 v82, v104, v55
	v_mul_f32_e32 v62, v54, v62
	v_mul_f32_e32 v92, v55, v202
	v_cvt_f32_f16_sdwa v54, v53 dst_sel:DWORD dst_unused:UNUSED_PAD src0_sel:WORD_1
	v_cvt_f32_f16_sdwa v55, v57 dst_sel:DWORD dst_unused:UNUSED_PAD src0_sel:WORD_1
	v_mul_f32_e32 v71, 0xbfb8aa3b, v71
	v_exp_f32_e32 v63, v63
	v_mul_f32_e32 v70, 0xbfb8aa3b, v70
	v_sub_f32_e32 v55, v55, v54
	v_fma_mix_f32 v55, v55, v87, v53 op_sel:[0,0,1] op_sel_hi:[0,0,1]
	v_sub_f32_e32 v54, v93, v54
	v_sub_f32_e32 v87, v111, v69
	v_fmac_f32_e32 v55, v54, v91
	v_mul_f32_e32 v54, 0x3fb8aa3b, v69
	v_mul_f32_e32 v87, 0x3fb8aa3b, v87
	v_mul_f32_e32 v69, 0xbfb8aa3b, v69
	v_exp_f32_e32 v54, v54
	v_exp_f32_e32 v87, v87
	v_exp_f32_e32 v69, v69
	v_exp_f32_e32 v58, v58
	v_mul_f32_e32 v65, v65, v54
	v_mul_f32_e32 v81, v81, v87
	v_mul_f32_e32 v69, v55, v69
	v_mul_f32_e32 v87, v54, v115
	v_cvt_f32_f16_e32 v54, v53
	v_cvt_f32_f16_e32 v55, v57
	v_cvt_f32_f16_e32 v57, v61
	v_exp_f32_e32 v71, v71
	v_exp_f32_e32 v70, v70
	v_sub_f32_e32 v55, v55, v54
	v_fma_mix_f32 v53, v55, v86, v53 op_sel_hi:[0,0,1]
	v_sub_f32_e32 v54, v57, v54
	v_fmac_f32_e32 v53, v54, v90
	v_mul_f32_e32 v54, 0x3fb8aa3b, v114
	v_mul_f32_e32 v57, 0xbfb8aa3b, v114
	v_exp_f32_e32 v54, v54
	v_exp_f32_e32 v57, v57
	v_cvt_f32_f16_sdwa v90, v60 dst_sel:DWORD dst_unused:UNUSED_PAD src0_sel:WORD_1
	v_sub_f32_e32 v55, v199, v114
	v_mul_f32_e32 v61, v110, v54
	v_mul_f32_e32 v57, v53, v57
	v_mul_f32_e32 v86, v54, v201
	v_cvt_f32_f16_sdwa v53, v52 dst_sel:DWORD dst_unused:UNUSED_PAD src0_sel:WORD_1
	v_cvt_f32_f16_sdwa v54, v56 dst_sel:DWORD dst_unused:UNUSED_PAD src0_sel:WORD_1
	v_mul_f32_e32 v55, 0x3fb8aa3b, v55
	v_exp_f32_e32 v55, v55
	v_mul_f32_e32 v63, v195, v63
	v_sub_f32_e32 v54, v54, v53
	v_fma_mix_f32 v54, v54, v85, v52 op_sel:[0,0,1] op_sel_hi:[0,0,1]
	v_sub_f32_e32 v53, v90, v53
	v_fmac_f32_e32 v54, v53, v89
	v_mul_f32_e32 v53, 0x3fb8aa3b, v68
	v_sub_f32_e32 v85, v113, v68
	v_mul_f32_e32 v68, 0xbfb8aa3b, v68
	v_mul_f32_e32 v85, 0x3fb8aa3b, v85
	v_exp_f32_e32 v68, v68
	v_exp_f32_e32 v53, v53
	v_exp_f32_e32 v85, v85
	v_mul_f32_e32 v58, v203, v58
	v_mul_f32_e32 v68, v54, v68
	v_cvt_f32_f16_e32 v54, v56
	v_cvt_f32_f16_e32 v56, v52
	v_mul_f32_e32 v80, v80, v85
	v_mul_f32_e32 v64, v64, v53
	v_mul_f32_e32 v85, v53, v196
	v_lshlrev_b32_e32 v53, 1, v140
	v_add3_u32 v102, v135, v171, v53
	v_cvt_f32_f16_e32 v53, v60
	v_sub_f32_e32 v54, v54, v56
	v_fma_mix_f32 v52, v54, v84, v52 op_sel_hi:[0,0,1]
	v_sub_f32_e32 v54, v137, v136
	v_sub_f32_e32 v53, v53, v56
	v_mul_f32_e32 v54, 0x3fb8aa3b, v54
	v_fmac_f32_e32 v52, v53, v88
	v_mul_f32_e32 v53, 0x3fb8aa3b, v136
	v_exp_f32_e32 v54, v54
	v_mul_f32_e32 v56, 0xbfb8aa3b, v136
	v_exp_f32_e32 v53, v53
	v_exp_f32_e32 v56, v56
	v_mul_f32_e32 v55, v200, v55
	v_mul_f32_e32 v54, v138, v54
	v_mul_f32_e32 v71, v99, v71
	v_mul_f32_e32 v70, v95, v70
	v_mul_f32_e32 v56, v52, v56
	v_mul_f32_e32 v60, v112, v53
	v_mul_f32_e32 v84, v53, v139
	v_cvt_pk_bf16_f32 v52, v54, v80
	v_cvt_pk_bf16_f32 v53, v55, v81
	v_cvt_pk_bf16_f32 v54, v58, v74
	v_cvt_pk_bf16_f32 v55, v63, v75
	ds_write_b128 v102, v[52:55]
	v_cvt_pk_bf16_f32 v52, v56, v68
	v_cvt_pk_bf16_f32 v53, v57, v69
	v_cvt_pk_bf16_f32 v54, v62, v70
	v_cvt_pk_bf16_f32 v55, v83, v71
	v_mov_b32_e32 v161, v34
	v_mul_f32_e32 v59, v59, v194
	ds_write_b128 v102, v[52:55] offset:2304
	v_cvt_pk_bf16_f32 v52, v60, v64
	v_cvt_pk_bf16_f32 v53, v61, v65
	v_cvt_pk_bf16_f32 v54, v82, v66
	v_cvt_pk_bf16_f32 v55, v94, v67
	v_lshl_add_u64 v[72:73], s[60:61], 0, v[160:161]
	v_lshl_add_u64 v[76:77], s[68:69], 0, v[160:161]
	ds_write_b128 v162, v[52:55]
	v_cvt_pk_bf16_f32 v52, v84, v85
	v_cvt_pk_bf16_f32 v53, v86, v87
	v_cvt_pk_bf16_f32 v54, v92, v78
	v_cvt_pk_bf16_f32 v55, v59, v79
	ds_write_b128 v162, v[52:55] offset:2304
	global_load_dwordx4 v[64:67], v[72:73], off offset:48
	global_load_dwordx4 v[56:59], v[72:73], off offset:32
	global_load_dwordx4 v[60:63], v[76:77], off offset:48
	global_load_dwordx4 v[52:55], v[76:77], off offset:32
	global_load_dwordx4 v[68:71], v[72:73], off offset:2096
	global_load_dwordx4 v[84:87], v[72:73], off offset:2080
	s_nop 0
	global_load_dwordx4 v[72:75], v[76:77], off offset:2096
	global_load_dwordx4 v[88:91], v[76:77], off offset:2080
	s_nop 0
	global_load_dwordx4 v[76:79], v182, s[60:61] offset:16
	global_load_dwordx4 v[92:95], v182, s[60:61]
	s_waitcnt vmcnt(10)
	v_cvt_f32_f16_e32 v80, v36
	v_cvt_f32_f16_e32 v103, v48
	s_waitcnt vmcnt(4)
	v_fmac_f32_e32 v192, v134, v84
	s_waitcnt vmcnt(2)
	v_fmac_f32_e32 v192, v133, v88
	v_cvt_f32_f16_e32 v88, v30
	v_cvt_f32_f16_e32 v84, v40
	v_sub_f32_e32 v80, v80, v88
	s_waitcnt vmcnt(0)
	v_fma_mix_f32 v105, v80, v92, v30 op_sel_hi:[0,0,1]
	global_load_dwordx4 v[80:83], v182, s[68:69] offset:16
	global_load_dwordx4 v[96:99], v182, s[68:69]
	v_sub_f32_e32 v84, v84, v88
	v_cvt_f32_f16_e32 v88, v44
	s_waitcnt vmcnt(0)
	v_fmac_f32_e32 v105, v84, v96
	v_add_f32_dpp v84, v88, v88 row_shr:1 row_mask:0xf bank_mask:0xf bound_ctrl:1
	v_cvt_pk_bf16_f32 v105, v105, s0
	s_nop 0
	v_add_f32_dpp v84, v84, v84 row_shr:2 row_mask:0xf bank_mask:0xf bound_ctrl:1
	s_nop 1
	v_add_f32_dpp v84, v84, v84 row_shr:4 row_mask:0xf bank_mask:0xf bound_ctrl:1
	s_nop 1
	v_add_f32_dpp v92, v84, v84 row_shr:8 row_mask:0xf bank_mask:0xf bound_ctrl:1
	s_waitcnt vmcnt(0)
	v_mul_f32_e32 v84, v192, v246
	v_mul_f32_e32 v96, v118, v84
	v_mov_b32_dpp v104, v92 row_newbcast:15 row_mask:0xf bank_mask:0xf bound_ctrl:1
	v_mul_f32_e32 v84, v96, v103
	v_add_f32_e32 v103, -1.0, v103
	v_fma_f32 v103, v103, v14, 1.0
	v_sub_f32_e32 v106, v92, v104
	v_mul_f32_e32 v106, 0x3fb8aa3b, v106
	v_exp_f32_e32 v106, v106
	v_mul_f32_e32 v103, v192, v103
	v_mul_f32_e32 v107, v106, v84
	v_mul_f32_e32 v106, v106, v103
	v_cvt_pk_bf16_f32 v107, v107, s0
	v_cvt_pk_bf16_f32 v106, v106, s0
	ds_write_b16 v109, v107 offset:5168
	ds_write_b16 v109, v106 offset:5176
	ds_write_b16 v108, v105 offset:10064
	s_and_saveexec_b64 s[58:59], s[40:41]
	s_cbranch_execz .LBB0_349
	v_mul_f32_e32 v104, 0xbfb8aa3b, v104
	v_exp_f32_e32 v104, v104
	v_lshl_add_u32 v105, v140, 2, v35
	ds_write_b32 v105, v104 offset:12832

.LBB0_363:
	s_or_b64 exec, exec, s[58:59]
	v_sub_f32_e32 v39, v39, v33
	v_mul_f32_e32 v39, 0x3fb8aa3b, v39
	v_exp_f32_e32 v39, v39
	v_cvt_f32_f16_sdwa v43, v21 dst_sel:DWORD dst_unused:UNUSED_PAD src0_sel:WORD_1
	v_cvt_f32_f16_sdwa v75, v25 dst_sel:DWORD dst_unused:UNUSED_PAD src0_sel:WORD_1
	v_cvt_f32_f16_e32 v25, v25
	v_mul_f32_e32 v39, v51, v39
	v_cvt_f32_f16_e32 v51, v21
	v_cvt_f32_f16_sdwa v78, v29 dst_sel:DWORD dst_unused:UNUSED_PAD src0_sel:WORD_1
	v_cvt_f32_f16_e32 v29, v29
	v_sub_f32_e32 v75, v75, v43
	v_sub_f32_e32 v25, v25, v51
	v_fma_mix_f32 v67, v75, v67, v21 op_sel:[0,0,1] op_sel_hi:[0,0,1]
	v_fma_mix_f32 v21, v25, v66, v21 op_sel_hi:[0,0,1]
	v_sub_f32_e32 v25, v29, v51
	v_mul_f32_e32 v29, 0xbfb8aa3b, v69
	v_exp_f32_e32 v29, v29
	v_fmac_f32_e32 v21, v25, v62
	v_cvt_f32_f16_sdwa v62, v24 dst_sel:DWORD dst_unused:UNUSED_PAD src0_sel:WORD_1
	v_cvt_f32_f16_sdwa v66, v28 dst_sel:DWORD dst_unused:UNUSED_PAD src0_sel:WORD_1
	v_mul_f32_e32 v29, v21, v29
	v_cvt_f32_f16_sdwa v21, v20 dst_sel:DWORD dst_unused:UNUSED_PAD src0_sel:WORD_1
	v_cvt_f32_f16_e32 v24, v24
	v_cvt_f32_f16_e32 v28, v28
	v_sub_f32_e32 v25, v70, v69
	v_sub_f32_e32 v62, v62, v21
	v_fma_mix_f32 v62, v62, v65, v20 op_sel:[0,0,1] op_sel_hi:[0,0,1]
	v_sub_f32_e32 v21, v66, v21
	v_fmac_f32_e32 v62, v21, v61
	v_sub_f32_e32 v21, v38, v32
	v_mul_f32_e32 v21, 0x3fb8aa3b, v21
	v_exp_f32_e32 v21, v21
	v_mul_f32_e32 v38, 0xbfb8aa3b, v32
	v_mul_f32_e32 v32, 0x3fb8aa3b, v32
	v_exp_f32_e32 v32, v32
	v_mul_f32_e32 v21, v46, v21
	v_cvt_f32_f16_e32 v46, v20
	v_cvt_f32_f16_sdwa v61, v27 dst_sel:DWORD dst_unused:UNUSED_PAD src0_sel:WORD_1
	v_mul_f32_e32 v42, v32, v42
	v_mul_f32_e32 v32, v32, v50
	v_sub_f32_e32 v24, v24, v46
	v_fma_mix_f32 v20, v24, v64, v20 op_sel_hi:[0,0,1]
	v_sub_f32_e32 v24, v28, v46
	v_mul_f32_e32 v28, 0xbfb8aa3b, v68
	v_exp_f32_e32 v28, v28
	v_fmac_f32_e32 v20, v24, v60
	v_cvt_f32_f16_sdwa v50, v23 dst_sel:DWORD dst_unused:UNUSED_PAD src0_sel:WORD_1
	v_cvt_f32_f16_e32 v23, v23
	v_mul_f32_e32 v28, v20, v28
	v_cvt_f32_f16_sdwa v20, v19 dst_sel:DWORD dst_unused:UNUSED_PAD src0_sel:WORD_1
	v_cvt_f32_f16_e32 v27, v27
	v_sub_f32_e32 v24, v72, v68
	v_sub_f32_e32 v43, v78, v43
	v_sub_f32_e32 v50, v50, v20
	v_fma_mix_f32 v50, v50, v59, v19 op_sel:[0,0,1] op_sel_hi:[0,0,1]
	v_sub_f32_e32 v20, v61, v20
	v_fmac_f32_e32 v50, v20, v55
	v_sub_f32_e32 v20, v37, v31
	v_mul_f32_e32 v20, 0x3fb8aa3b, v20
	v_exp_f32_e32 v20, v20
	v_mul_f32_e32 v37, 0xbfb8aa3b, v31
	v_mul_f32_e32 v31, 0x3fb8aa3b, v31
	v_exp_f32_e32 v31, v31
	v_mul_f32_e32 v20, v45, v20
	v_cvt_f32_f16_e32 v45, v19
	v_mul_f32_e32 v25, 0x3fb8aa3b, v25
	v_mul_f32_e32 v41, v31, v41
	v_mul_f32_e32 v31, v31, v49
	v_sub_f32_e32 v23, v23, v45
	v_fma_mix_f32 v19, v23, v58, v19 op_sel_hi:[0,0,1]
	v_sub_f32_e32 v23, v27, v45
	v_mul_f32_e32 v27, 0xbfb8aa3b, v85
	v_exp_f32_e32 v27, v27
	v_fmac_f32_e32 v19, v23, v54
	v_cvt_f32_f16_sdwa v49, v22 dst_sel:DWORD dst_unused:UNUSED_PAD src0_sel:WORD_1
	v_cvt_f32_f16_sdwa v54, v26 dst_sel:DWORD dst_unused:UNUSED_PAD src0_sel:WORD_1
	v_mul_f32_e32 v27, v19, v27
	v_cvt_f32_f16_sdwa v19, v18 dst_sel:DWORD dst_unused:UNUSED_PAD src0_sel:WORD_1
	v_cvt_f32_f16_e32 v22, v22
	v_cvt_f32_f16_e32 v26, v26
	v_sub_f32_e32 v23, v86, v85
	v_sub_f32_e32 v49, v49, v19
	v_fma_mix_f32 v49, v49, v57, v18 op_sel:[0,0,1] op_sel_hi:[0,0,1]
	v_sub_f32_e32 v19, v54, v19
	v_fmac_f32_e32 v49, v19, v53
	v_sub_f32_e32 v19, v36, v30
	v_mul_f32_e32 v19, 0x3fb8aa3b, v19
	v_exp_f32_e32 v19, v19
	v_mul_f32_e32 v36, 0xbfb8aa3b, v30
	v_mul_f32_e32 v30, 0x3fb8aa3b, v30
	v_exp_f32_e32 v30, v30
	v_mul_f32_e32 v19, v44, v19
	v_cvt_f32_f16_e32 v44, v18
	v_mul_f32_e32 v24, 0x3fb8aa3b, v24
	v_mul_f32_e32 v23, 0x3fb8aa3b, v23
	v_fmac_f32_e32 v67, v43, v63
	v_sub_f32_e32 v22, v22, v44
	v_fma_mix_f32 v18, v22, v56, v18 op_sel_hi:[0,0,1]
	v_sub_f32_e32 v22, v26, v44
	v_sub_f32_e32 v44, v88, v92
	v_mul_f32_e32 v44, 0x3fb8aa3b, v44
	v_mul_f32_e32 v43, 0xbfb8aa3b, v33
	v_exp_f32_e32 v25, v25
	v_exp_f32_e32 v24, v24
	v_exp_f32_e32 v23, v23
	v_mul_f32_e32 v40, v30, v40
	v_mul_f32_e32 v30, v30, v48
	v_exp_f32_e32 v44, v44
	v_mul_f32_e32 v48, 0xbfb8aa3b, v92
	v_exp_f32_e32 v43, v43
	v_mul_f32_e32 v33, 0x3fb8aa3b, v33
	v_mul_f32_e32 v51, 0x3fb8aa3b, v69
	v_exp_f32_e32 v38, v38
	v_mul_f32_e32 v46, 0x3fb8aa3b, v68
	v_exp_f32_e32 v37, v37
	v_mul_f32_e32 v45, 0x3fb8aa3b, v85
	v_exp_f32_e32 v36, v36
	v_mul_f32_e32 v26, 0x3fb8aa3b, v92
	v_exp_f32_e32 v48, v48
	v_exp_f32_e32 v33, v33
	v_exp_f32_e32 v51, v51
	v_exp_f32_e32 v46, v46
	v_exp_f32_e32 v45, v45
	v_exp_f32_e32 v26, v26
	v_mul_f32_e32 v25, v74, v25
	v_mul_f32_e32 v24, v80, v24
	v_mul_f32_e32 v23, v90, v23
	v_fmac_f32_e32 v18, v22, v52
	v_mul_f32_e32 v22, v96, v44
	v_mul_f32_e32 v43, v67, v43
	v_mul_f32_e32 v38, v62, v38
	v_mul_f32_e32 v37, v50, v37
	v_mul_f32_e32 v36, v49, v36
	v_mul_f32_e32 v44, v18, v48
	v_cvt_pk_bf16_f32 v18, v22, v19
	v_cvt_pk_bf16_f32 v19, v23, v20
	v_cvt_pk_bf16_f32 v20, v24, v21
	v_cvt_pk_bf16_f32 v21, v25, v39
	v_mul_f32_e32 v47, v33, v47
	v_mul_f32_e32 v63, v51, v73
	v_mul_f32_e32 v60, v46, v76
	v_mul_f32_e32 v50, v45, v89
	v_mul_f32_e32 v48, v26, v84
	ds_write_b128 v102, v[18:21] offset:16
	v_cvt_pk_bf16_f32 v18, v44, v36
	v_cvt_pk_bf16_f32 v19, v27, v37
	v_cvt_pk_bf16_f32 v20, v28, v38
	v_cvt_pk_bf16_f32 v21, v29, v43
	v_mul_f32_e32 v33, v33, v71
	v_mul_f32_e32 v51, v51, v77
	v_mul_f32_e32 v46, v46, v87
	v_mul_f32_e32 v45, v45, v93
	v_mul_f32_e32 v26, v26, v103
	ds_write_b128 v102, v[18:21] offset:2320
	v_cvt_pk_bf16_f32 v18, v48, v40
	v_cvt_pk_bf16_f32 v19, v50, v41
	v_cvt_pk_bf16_f32 v20, v60, v42
	v_cvt_pk_bf16_f32 v21, v63, v47
	ds_write_b128 v162, v[18:21] offset:16
	v_cvt_pk_bf16_f32 v18, v26, v30
	v_cvt_pk_bf16_f32 v19, v45, v31
	v_cvt_pk_bf16_f32 v20, v46, v32
	v_cvt_pk_bf16_f32 v21, v51, v33
	ds_write_b128 v162, v[18:21] offset:2320
	s_add_i32 s98, s97, 1
	s_cmp_ge_i32 s98, s96
	s_cbranch_scc1 .Lspf_skip1
	v_lshl_add_u32 v22, s98, 6, v151
	v_sub_u32_e32 v23, 0x7ff, v22
	v_cndmask_b32_e64 v24, v23, v22, s[56:57]
	v_ashrrev_i32_e32 v25, 31, v24
	v_lshl_add_u64 v[22:23], s[22:23], 0, v[24:25]
	v_mov_b64_e32 v[26:27], s[30:31]
	v_mad_u64_u32 v[28:29], s[100:101], v22, s89, v[26:27]
	v_mad_i32_i24 v29, v23, s89, v29
	v_lshlrev_b32_e32 v30, 1, v148
	v_mov_b32_e32 v31, v34
	v_lshl_add_u64 v[28:29], v[28:29], 0, v[30:31]
	s_mov_b64 s[100:101], 0x1000
	v_lshl_add_u64 v[30:31], v[28:29], 0, s[100:101]
	s_mov_b64 s[100:101], 0x3000
	v_lshl_add_u64 v[32:33], v[28:29], 0, s[100:101]
	v_lshl_add_u64 v[22:23], v[22:23], 0, s[24:25]
	v_lshlrev_b64 v[22:23], 10, v[22:23]
	v_lshl_add_u64 v[26:27], v[154:155], 0, v[22:23]
	v_lshl_add_u64 v[22:23], v[156:157], 0, v[22:23]
	v_mov_b32_e32 v56, 0
	v_mov_b32_e32 v57, 0
	v_mov_b32_e32 v58, 0
	v_mov_b32_e32 v59, 0
	v_mov_b32_e32 v60, 0
	v_mov_b32_e32 v61, 0
	v_mov_b32_e32 v62, 0
	v_mov_b32_e32 v63, 0
	v_mov_b32_e32 v68, 0
	v_mov_b32_e32 v69, 0
	v_mov_b32_e32 v70, 0
	v_mov_b32_e32 v71, 0
	v_mov_b32_e32 v72, 0
	v_mov_b32_e32 v73, 0
	v_mov_b32_e32 v74, 0
	v_mov_b32_e32 v75, 0
	v_mov_b32_e32 v92, 0
	v_mov_b32_e32 v93, 0
	v_mov_b32_e32 v94, 0
	v_mov_b32_e32 v95, 0
	v_mov_b32_e32 v96, 0
	v_mov_b32_e32 v97, 0
	v_mov_b32_e32 v98, 0
	v_mov_b32_e32 v99, 0
	v_mov_b32_e32 v100, 0
	v_mov_b32_e32 v101, 0
	v_mov_b32_e32 v102, 0
	v_mov_b32_e32 v103, 0
	v_mov_b32_e32 v104, 0
	v_mov_b32_e32 v105, 0
	v_mov_b32_e32 v106, 0
	v_mov_b32_e32 v107, 0
	global_load_dwordx4 v[84:87], v[30:31], off offset:1024
	global_load_dwordx4 v[88:91], v[30:31], off offset:1040
	v_cmp_lt_i32_e32 vcc, 0, v24
	s_and_saveexec_b64 s[100:101], vcc
	global_load_dwordx4 v[96:99], v[28:29], off offset:-2816
	global_load_dwordx4 v[104:107], v[28:29], off offset:-2800
	s_mov_b64 exec, s[100:101]
	v_cmp_gt_i32_e32 vcc, 0x7ff, v24
	s_and_saveexec_b64 s[100:101], vcc
	global_load_dwordx4 v[92:95], v[32:33], off offset:768
	global_load_dwordx4 v[100:103], v[32:33], off offset:784
	s_mov_b64 exec, s[100:101]
	global_load_dwordx4 v[52:55], v[30:31], off
	global_load_dwordx4 v[64:67], v[30:31], off offset:2048
	global_load_dwordx4 v[76:79], v[26:27], off
	global_load_dwordx4 v[80:83], v[22:23], off
	v_cmp_lt_i32_e32 vcc, 0, v24
	s_and_saveexec_b64 s[100:101], vcc
	global_load_dwordx4 v[56:59], v[28:29], off offset:-3840
	global_load_dwordx4 v[68:71], v[28:29], off offset:-1792
	s_mov_b64 exec, s[100:101]
	v_cmp_gt_i32_e32 vcc, 0x7ff, v24
	s_and_saveexec_b64 s[100:101], vcc
	global_load_dwordx4 v[60:63], v[32:33], off offset:-256
	global_load_dwordx4 v[72:75], v[32:33], off offset:1792
	s_mov_b64 exec, s[100:101]
